# norm phases: the row-invariant gain vector is loaded once per phase instead of once per row pair
# speedup vs baseline: 1.0029x; 1.0029x over previous
.LBB0_146:
	v_mov_b32_e32 v0, v188
	v_mov_b32_e32 v2, 0x21d28
	v_mov_b32_e32 v4, 0x21c40
	v_add_u32_e32 v2, 0, v2
	ds_read_b64 v[2:3], v2
	v_mov_b32_e32 v6, 0x21d28
	v_add_u32_e32 v4, 0, v4
	ds_read_b64 v[4:5], v4
	v_ashrrev_i32_e32 v1, 6, v0
	v_add_u32_e32 v6, 0, v6
	ds_read_b64 v[6:7], v6
	v_readlane_b32 s0, v238, 7
	s_waitcnt lgkmcnt(2)
	v_readfirstlane_b32 s2, v3
	v_readfirstlane_b32 s4, v2
	v_add_u32_e32 v24, s0, v1
	s_mov_b32 s0, 0xa000
	s_waitcnt lgkmcnt(1)
	v_readfirstlane_b32 s5, v5
	v_readfirstlane_b32 s6, v4
	s_waitcnt lgkmcnt(0)
	v_readfirstlane_b32 s7, v7
	v_readfirstlane_b32 s8, v6
	v_cmp_gt_i32_e32 vcc, s0, v24
	s_mul_i32 s69, s52, 9
	s_and_saveexec_b64 s[0:1], vcc
	s_cbranch_execz .LBB0_169
	s_add_u32 s10, s8, 0x6078000
	s_addc_u32 s11, s7, 0
	s_lshl_b32 s7, s52, 13
	s_add_u32 s6, s6, s7
	s_addc_u32 s7, s5, 0
	v_lshlrev_b32_e32 v1, 2, v0
	s_add_u32 s4, s4, 0x2bc0000
	v_and_b32_e32 v26, 0xfc, v1
	v_ashrrev_i32_e32 v25, 31, v24
	s_addc_u32 s5, s2, 0
	v_lshlrev_b32_e32 v164, 2, v26
	v_lshlrev_b64 v[2:3], 11, v[24:25]
	v_and_b32_e32 v0, 63, v0
	s_cmp_lg_u32 s52, 0
	s_movk_i32 s2, 0x80
	v_lshl_add_u64 v[28:29], s[6:7], 0, v[164:165]
	v_lshlrev_b32_e32 v164, 1, v26
	v_lshl_or_b32 v2, v0, 3, v2
	s_cselect_b64 s[8:9], -1, 0
	v_bitop3_b32 v27, v1, s2, v193 bitop3:0x6c
	v_or_b32_e32 v30, 0x100, v26
	v_or_b32_e32 v32, 0x200, v26
	v_or_b32_e32 v34, 0x300, v26
	v_lshl_add_u64 v[36:37], s[10:11], 0, v[164:165]
	v_lshl_add_u64 v[38:39], s[10:11], 0, v[2:3]
	s_mov_b64 s[10:11], 0
	s_mov_b64 s[12:13], 0
	v_mov_b32_e32 v40, v24
	global_load_dwordx4 v[198:201], v[28:29], off
	global_load_dwordx4 v[202:205], v[28:29], off offset:1024
	global_load_dwordx4 v[206:209], v[28:29], off offset:2048
	global_load_dwordx4 v[210:213], v[28:29], off offset:3072
	s_branch .LBB0_149

.LBB0_167:
	s_or_b64 exec, exec, s[14:15]
	v_add_u32_e32 v31, 0xffffe000, v40
	v_lshrrev_b32_e32 v31, 12, v31
	v_add_u32_e32 v31, 1, v31
	v_cmp_lt_i32_e32 vcc, s48, v40
	v_mov_b64_e32 v[70:71], s[4:5]
	s_waitcnt vmcnt(3)
	v_mov_b32_e32 v86, v21
	v_cndmask_b32_e32 v31, 0, v31, vcc
	v_add_u32_e32 v31, s69, v31
	v_mad_u64_u32 v[74:75], s[6:7], v31, s50, v[70:71]
	v_lshl_add_u64 v[82:83], v[74:75], 0, s[58:59]
	v_lshl_add_u64 v[84:85], v[74:75], 0, v[164:165]
	v_lshl_add_u64 v[78:79], v[82:83], 0, v[164:165]
	s_nop 0
	v_mov_b32_e32 v252, v78
	v_mov_b32_e32 v253, v79
	global_load_dwordx4 v[214:217], v[84:85], off
	global_load_dwordx4 v[218:221], v[84:85], off offset:1024
	global_load_dwordx4 v[222:225], v[84:85], off offset:2048
	global_load_dwordx4 v[226:229], v[84:85], off offset:3072
	global_load_dwordx4 v[230:233], v[252:253], off
	global_load_dwordx4 v[240:243], v[252:253], off offset:1024
	global_load_dwordx4 v[244:247], v[252:253], off offset:2048
	global_load_dwordx4 v[248:251], v[252:253], off offset:3072
	s_waitcnt vmcnt(0)
	v_mov_b32_e32 v70, v198
	v_mov_b32_e32 v71, v199
	v_mov_b32_e32 v72, v200
	v_mov_b32_e32 v73, v201
	v_mov_b32_e32 v74, v214
	v_mov_b32_e32 v75, v215
	v_mov_b32_e32 v76, v216
	v_mov_b32_e32 v77, v217
	v_mov_b32_e32 v78, v230
	v_mov_b32_e32 v79, v231
	v_mov_b32_e32 v80, v232
	v_mov_b32_e32 v81, v233
	v_mov_b32_e32 v87, v17
	v_mov_b32_e32 v68, v20
	v_mov_b32_e32 v69, v16
	v_pk_mul_f32 v[86:87], v[86:87], v[86:87]
	v_mov_b32_e32 v88, v22
	v_mov_b32_e32 v89, v18
	v_pk_fma_f32 v[68:69], v[68:69], v[68:69], v[86:87]
	v_mov_b32_e32 v90, v23
	v_pk_fma_f32 v[68:69], v[88:89], v[88:89], v[68:69]
	v_mov_b32_e32 v88, v13
	v_mov_b32_e32 v89, v9
	v_mov_b32_e32 v91, v19
	v_mov_b32_e32 v86, v12
	v_mov_b32_e32 v87, v8
	v_pk_mul_f32 v[88:89], v[88:89], v[88:89]
	v_pk_fma_f32 v[68:69], v[90:91], v[90:91], v[68:69]
	v_mov_b32_e32 v90, v14
	v_mov_b32_e32 v91, v10
	v_pk_fma_f32 v[86:87], v[86:87], v[86:87], v[88:89]
	v_mov_b32_e32 v92, v15
	v_mov_b32_e32 v93, v11
	v_pk_fma_f32 v[86:87], v[90:91], v[90:91], v[86:87]
	v_add_f32_e32 v31, v68, v69
	v_pk_fma_f32 v[86:87], v[92:93], v[92:93], v[86:87]
	v_lshlrev_b32_e32 v68, 2, v30
	v_add_f32_e32 v31, v31, v86
	v_add_f32_e32 v31, v31, v87
	ds_bpermute_b32 v33, v27, v31
	v_mov_b32_e32 v69, v165
	v_lshl_add_u64 v[86:87], v[82:83], 0, v[68:69]
	s_waitcnt lgkmcnt(0)
	v_add_f32_e32 v31, v31, v33
	ds_swizzle_b32 v33, v31 offset:swizzle(SWAP,16)
	s_waitcnt lgkmcnt(0)
	v_add_f32_e32 v31, v31, v33
	ds_swizzle_b32 v33, v31 offset:swizzle(SWAP,8)
	s_waitcnt lgkmcnt(0)
	v_add_f32_e32 v31, v31, v33
	ds_swizzle_b32 v33, v31 offset:swizzle(SWAP,4)
	s_waitcnt lgkmcnt(0)
	v_add_f32_e32 v31, v31, v33
	ds_swizzle_b32 v33, v31 offset:swizzle(SWAP,2)
	s_waitcnt lgkmcnt(0)
	v_add_f32_e32 v31, v31, v33
	ds_swizzle_b32 v33, v31 offset:swizzle(SWAP,1)
	s_waitcnt lgkmcnt(0)
	v_add_f32_e32 v31, v31, v33
	v_fmamk_f32 v31, v31, 0x3a800000, v189
	v_mul_f32_e32 v33, 0x4b800000, v31
	v_cmp_gt_f32_e32 vcc, s28, v31
	v_add_f32_e32 v35, 1.0, v79
	s_nop 0
	v_cndmask_b32_e32 v31, v31, v33, vcc
	v_rsq_f32_e32 v31, v31
	v_add_f32_e32 v41, 1.0, v80
	v_add_f32_e32 v51, 1.0, v81
	v_mul_f32_e32 v33, 0x45800000, v31
	v_cndmask_b32_e32 v31, v31, v33, vcc
	v_mul_f32_e32 v20, v20, v31
	v_mul_f32_e32 v21, v21, v31
	v_mul_f32_e32 v22, v22, v31
	v_mul_f32_e32 v23, v23, v31
	v_mul_f32_e32 v20, v70, v20
	v_mul_f32_e32 v21, v71, v21
	v_add_f32_e32 v33, 1.0, v78
	v_mul_f32_e32 v22, v72, v22
	v_mul_f32_e32 v23, v73, v23
	v_fma_f32 v20, v33, v20, v74
	v_fma_f32 v21, v35, v21, v75
	v_fma_f32 v22, v22, v41, v76
	v_fmac_f32_e32 v77, v23, v51
	v_cvt_pk_bf16_f32 v20, v20, v21
	v_cvt_pk_bf16_f32 v21, v22, v77
	global_store_dwordx2 v[38:39], v[20:21], off
	v_mov_b32_e32 v70, v202
	v_mov_b32_e32 v71, v203
	v_mov_b32_e32 v72, v204
	v_mov_b32_e32 v73, v205
	v_mov_b32_e32 v74, v240
	v_mov_b32_e32 v75, v241
	v_mov_b32_e32 v76, v242
	v_mov_b32_e32 v77, v243
	v_mov_b32_e32 v78, v218
	v_mov_b32_e32 v79, v219
	v_mov_b32_e32 v80, v220
	v_mov_b32_e32 v81, v221
	v_mul_f32_e32 v16, v16, v31
	v_mul_f32_e32 v17, v17, v31
	v_mul_f32_e32 v18, v18, v31
	v_mul_f32_e32 v19, v19, v31
	v_lshlrev_b32_e32 v20, 2, v32
	v_mov_b32_e32 v21, v165
	v_lshl_add_u64 v[22:23], v[82:83], 0, v[20:21]
	v_mul_f32_e32 v12, v12, v31
	v_mul_f32_e32 v13, v13, v31
	v_mul_f32_e32 v14, v14, v31
	v_mul_f32_e32 v15, v15, v31
	v_mul_f32_e32 v8, v8, v31
	v_mul_f32_e32 v9, v9, v31
	v_mul_f32_e32 v10, v10, v31
	v_mul_f32_e32 v11, v11, v31
	v_mul_f32_e32 v16, v16, v70
	v_add_f32_e32 v33, 1.0, v74
	v_mul_f32_e32 v17, v17, v71
	v_add_f32_e32 v35, 1.0, v75
	v_mul_f32_e32 v18, v18, v72
	v_add_f32_e32 v41, 1.0, v76
	v_mul_f32_e32 v19, v19, v73
	v_add_f32_e32 v51, 1.0, v77
	v_fma_f32 v16, v16, v33, v78
	v_fma_f32 v17, v17, v35, v79
	v_fma_f32 v18, v18, v41, v80
	v_fmac_f32_e32 v81, v19, v51
	v_cvt_pk_bf16_f32 v16, v16, v17
	v_cvt_pk_bf16_f32 v17, v18, v81
	global_store_dwordx2 v[38:39], v[16:17], off offset:512
	v_mov_b32_e32 v70, v206
	v_mov_b32_e32 v71, v207
	v_mov_b32_e32 v72, v208
	v_mov_b32_e32 v73, v209
	v_mov_b32_e32 v74, v244
	v_mov_b32_e32 v75, v245
	v_mov_b32_e32 v76, v246
	v_mov_b32_e32 v77, v247
	v_mov_b32_e32 v78, v222
	v_mov_b32_e32 v79, v223
	v_mov_b32_e32 v80, v224
	v_mov_b32_e32 v81, v225
	v_lshlrev_b32_e32 v16, 2, v34
	v_mov_b32_e32 v17, v165
	v_lshl_add_u64 v[18:19], v[82:83], 0, v[16:17]
	v_mul_f32_e32 v12, v12, v70
	v_add_f32_e32 v22, 1.0, v74
	v_mul_f32_e32 v13, v13, v71
	v_add_f32_e32 v23, 1.0, v75
	v_mul_f32_e32 v14, v14, v72
	v_add_f32_e32 v33, 1.0, v76
	v_mul_f32_e32 v15, v15, v73
	v_add_f32_e32 v35, 1.0, v77
	v_fma_f32 v12, v12, v22, v78
	v_fma_f32 v13, v13, v23, v79
	v_fma_f32 v14, v14, v33, v80
	v_fmac_f32_e32 v81, v15, v35
	v_cvt_pk_bf16_f32 v12, v12, v13
	v_cvt_pk_bf16_f32 v13, v14, v81
	global_store_dwordx2 v[38:39], v[12:13], off offset:1024
	v_mov_b32_e32 v12, v210
	v_mov_b32_e32 v13, v211
	v_mov_b32_e32 v14, v212
	v_mov_b32_e32 v15, v213
	s_nop 0
	v_mov_b32_e32 v70, v248
	v_mov_b32_e32 v71, v249
	v_mov_b32_e32 v72, v250
	v_mov_b32_e32 v73, v251
	v_mov_b32_e32 v74, v226
	v_mov_b32_e32 v75, v227
	v_mov_b32_e32 v76, v228
	v_mov_b32_e32 v77, v229
	v_mul_f32_e32 v8, v8, v12
	v_add_f32_e32 v12, 1.0, v70
	v_mul_f32_e32 v9, v9, v13
	v_add_f32_e32 v13, 1.0, v71
	v_mul_f32_e32 v10, v10, v14
	v_add_f32_e32 v14, 1.0, v72
	v_mul_f32_e32 v11, v11, v15
	v_add_f32_e32 v15, 1.0, v73
	v_fma_f32 v8, v8, v12, v74
	v_fma_f32 v9, v9, v13, v75
	v_fma_f32 v10, v10, v14, v76
	v_fmac_f32_e32 v77, v11, v15
	v_cvt_pk_bf16_f32 v8, v8, v9
	v_cvt_pk_bf16_f32 v9, v10, v77
	global_store_dwordx2 v[38:39], v[8:9], off offset:1536
	s_and_saveexec_b64 s[14:15], s[34:35]
	s_cbranch_execz .LBB0_148
	v_add_u32_e32 v8, 0xffffe000, v50
	v_lshrrev_b32_e32 v8, 12, v8
	v_add_u32_e32 v8, 1, v8
	v_cmp_lt_i32_e32 vcc, s48, v50
	v_mov_b64_e32 v[12:13], s[4:5]
	v_pk_mul_f32 v[60:61], v[60:61], v[60:61]
	v_cndmask_b32_e32 v8, 0, v8, vcc
	v_add_u32_e32 v14, s69, v8
	v_mad_u64_u32 v[18:19], s[6:7], v14, s50, v[12:13]
	v_lshl_add_u64 v[22:23], v[18:19], 0, s[58:59]
	v_lshl_add_u64 v[12:13], v[22:23], 0, v[164:165]
	v_lshl_add_u64 v[74:75], v[18:19], 0, v[164:165]
	v_pk_mul_f32 v[18:19], v[66:67], v[66:67]
	v_mov_b32_e32 v254, v12
	v_mov_b32_e32 v255, v13
	global_load_dwordx4 v[214:217], v[74:75], off
	global_load_dwordx4 v[218:221], v[74:75], off offset:1024
	global_load_dwordx4 v[222:225], v[74:75], off offset:2048
	global_load_dwordx4 v[226:229], v[74:75], off offset:3072
	global_load_dwordx4 v[230:233], v[254:255], off
	global_load_dwordx4 v[240:243], v[254:255], off offset:1024
	global_load_dwordx4 v[244:247], v[254:255], off offset:2048
	global_load_dwordx4 v[248:251], v[254:255], off offset:3072
	s_waitcnt vmcnt(0)
	v_mov_b32_e32 v8, v198
	v_mov_b32_e32 v9, v199
	v_mov_b32_e32 v10, v200
	v_mov_b32_e32 v11, v201
	v_mov_b32_e32 v12, v230
	v_mov_b32_e32 v13, v231
	v_mov_b32_e32 v14, v232
	v_mov_b32_e32 v15, v233
	v_mov_b32_e32 v70, v214
	v_mov_b32_e32 v71, v215
	v_mov_b32_e32 v72, v216
	v_mov_b32_e32 v73, v217
	v_pk_fma_f32 v[18:19], v[64:65], v[64:65], v[18:19]
	v_pk_fma_f32 v[56:57], v[56:57], v[56:57], v[60:61]
	v_pk_fma_f32 v[18:19], v[62:63], v[62:63], v[18:19]
	v_pk_fma_f32 v[54:55], v[54:55], v[54:55], v[56:57]
	v_pk_fma_f32 v[18:19], v[58:59], v[58:59], v[18:19]
	v_pk_fma_f32 v[52:53], v[52:53], v[52:53], v[54:55]
	v_add_f32_e32 v18, v18, v19
	v_add_f32_e32 v18, v53, v18
	v_add_f32_e32 v18, v52, v18
	ds_bpermute_b32 v19, v27, v18
	v_ashrrev_i32_e32 v51, 31, v50
	v_lshl_add_u64 v[16:17], v[22:23], 0, v[16:17]
	s_waitcnt lgkmcnt(0)
	v_add_f32_e32 v18, v18, v19
	ds_swizzle_b32 v19, v18 offset:swizzle(SWAP,16)
	s_waitcnt lgkmcnt(0)
	v_add_f32_e32 v18, v18, v19
	ds_swizzle_b32 v19, v18 offset:swizzle(SWAP,8)
	s_waitcnt lgkmcnt(0)
	v_add_f32_e32 v18, v18, v19
	ds_swizzle_b32 v19, v18 offset:swizzle(SWAP,4)
	s_waitcnt lgkmcnt(0)
	v_add_f32_e32 v18, v18, v19
	ds_swizzle_b32 v19, v18 offset:swizzle(SWAP,2)
	s_waitcnt lgkmcnt(0)
	v_add_f32_e32 v18, v18, v19
	ds_swizzle_b32 v19, v18 offset:swizzle(SWAP,1)
	s_waitcnt lgkmcnt(0)
	v_add_f32_e32 v18, v18, v19
	v_fmamk_f32 v18, v18, 0x3a800000, v189
	v_mul_f32_e32 v19, 0x4b800000, v18
	v_cmp_gt_f32_e32 vcc, s28, v18
	v_add_f32_e32 v12, 1.0, v12
	s_nop 0
	v_cndmask_b32_e32 v18, v18, v19, vcc
	v_rsq_f32_e32 v31, v18
	v_lshlrev_b64 v[18:19], 11, v[50:51]
	v_add_f32_e32 v13, 1.0, v13
	v_lshl_add_u64 v[54:55], v[36:37], 0, v[18:19]
	v_mul_f32_e32 v33, 0x45800000, v31
	v_cndmask_b32_e32 v31, v31, v33, vcc
	v_mul_f32_e32 v33, v49, v31
	v_mul_f32_e32 v35, v5, v31
	v_mul_f32_e32 v41, v47, v31
	v_mul_f32_e32 v50, v7, v31
	v_mul_f32_e32 v8, v8, v33
	v_mul_f32_e32 v9, v9, v35
	v_mul_f32_e32 v10, v10, v41
	v_mul_f32_e32 v11, v11, v50
	v_add_f32_e32 v14, 1.0, v14
	v_add_f32_e32 v15, 1.0, v15
	v_fma_f32 v8, v12, v8, v70
	v_fma_f32 v9, v13, v9, v71
	v_fma_f32 v10, v10, v14, v72
	v_fmac_f32_e32 v73, v11, v15
	v_cvt_pk_bf16_f32 v8, v8, v9
	v_cvt_pk_bf16_f32 v9, v10, v73
	global_store_dwordx2 v[54:55], v[8:9], off
	v_lshl_add_u64 v[18:19], v[22:23], 0, v[68:69]
	v_mov_b32_e32 v8, v202
	v_mov_b32_e32 v9, v203
	v_mov_b32_e32 v10, v204
	v_mov_b32_e32 v11, v205
	v_mov_b32_e32 v12, v240
	v_mov_b32_e32 v13, v241
	v_mov_b32_e32 v14, v242
	v_mov_b32_e32 v15, v243
	v_mov_b32_e32 v50, v218
	v_mov_b32_e32 v51, v219
	v_mov_b32_e32 v52, v220
	v_mov_b32_e32 v53, v221
	v_lshl_add_u64 v[18:19], v[22:23], 0, v[20:21]
	v_mul_f32_e32 v20, v48, v31
	v_mul_f32_e32 v21, v4, v31
	v_mul_f32_e32 v33, v46, v31
	v_mul_f32_e32 v35, v6, v31
	v_mul_f32_e32 v22, v45, v31
	v_mul_f32_e32 v23, v1, v31
	v_mul_f32_e32 v8, v20, v8
	v_add_f32_e32 v12, 1.0, v12
	v_mul_f32_e32 v9, v21, v9
	v_add_f32_e32 v13, 1.0, v13
	v_mul_f32_e32 v10, v33, v10
	v_add_f32_e32 v14, 1.0, v14
	v_mul_f32_e32 v11, v35, v11
	v_add_f32_e32 v15, 1.0, v15
	v_fma_f32 v8, v8, v12, v50
	v_fma_f32 v9, v9, v13, v51
	v_fma_f32 v10, v10, v14, v52
	v_fmac_f32_e32 v53, v11, v15
	v_cvt_pk_bf16_f32 v8, v8, v9
	v_cvt_pk_bf16_f32 v9, v10, v53
	global_store_dwordx2 v[54:55], v[8:9], off offset:512
	v_mov_b32_e32 v8, v206
	v_mov_b32_e32 v9, v207
	v_mov_b32_e32 v10, v208
	v_mov_b32_e32 v11, v209
	s_nop 0
	v_mov_b32_e32 v12, v244
	v_mov_b32_e32 v13, v245
	v_mov_b32_e32 v14, v246
	v_mov_b32_e32 v15, v247
	s_nop 0
	v_mov_b32_e32 v18, v222
	v_mov_b32_e32 v19, v223
	v_mov_b32_e32 v20, v224
	v_mov_b32_e32 v21, v225
	v_mul_f32_e32 v33, v43, v31
	v_mul_f32_e32 v35, v3, v31
	v_mul_f32_e32 v8, v22, v8
	v_add_f32_e32 v12, 1.0, v12
	v_mul_f32_e32 v9, v23, v9
	v_add_f32_e32 v13, 1.0, v13
	v_mul_f32_e32 v10, v33, v10
	v_add_f32_e32 v14, 1.0, v14
	v_mul_f32_e32 v11, v35, v11
	v_add_f32_e32 v15, 1.0, v15
	v_fma_f32 v8, v8, v12, v18
	v_fma_f32 v9, v9, v13, v19
	v_fma_f32 v10, v10, v14, v20
	v_fmac_f32_e32 v21, v11, v15
	v_cvt_pk_bf16_f32 v8, v8, v9
	v_cvt_pk_bf16_f32 v9, v10, v21
	global_store_dwordx2 v[54:55], v[8:9], off offset:1024
	v_mov_b32_e32 v8, v210
	v_mov_b32_e32 v9, v211
	v_mov_b32_e32 v10, v212
	v_mov_b32_e32 v11, v213
	s_nop 0
	v_mov_b32_e32 v12, v248
	v_mov_b32_e32 v13, v249
	v_mov_b32_e32 v14, v250
	v_mov_b32_e32 v15, v251
	s_nop 0
	v_mov_b32_e32 v16, v226
	v_mov_b32_e32 v17, v227
	v_mov_b32_e32 v18, v228
	v_mov_b32_e32 v19, v229
	v_mul_f32_e32 v20, v44, v31
	v_mul_f32_e32 v21, v0, v31
	v_mul_f32_e32 v22, v42, v31
	v_mul_f32_e32 v23, v2, v31
	v_mul_f32_e32 v8, v20, v8
	v_add_f32_e32 v12, 1.0, v12
	v_mul_f32_e32 v9, v21, v9
	v_add_f32_e32 v13, 1.0, v13
	v_mul_f32_e32 v10, v22, v10
	v_add_f32_e32 v14, 1.0, v14
	v_mul_f32_e32 v11, v23, v11
	v_add_f32_e32 v15, 1.0, v15
	v_fma_f32 v8, v8, v12, v16
	v_fma_f32 v9, v9, v13, v17
	v_fma_f32 v10, v10, v14, v18
	v_fmac_f32_e32 v19, v11, v15
	v_cvt_pk_bf16_f32 v8, v8, v9
	v_cvt_pk_bf16_f32 v9, v10, v19
	global_store_dwordx2 v[54:55], v[8:9], off offset:1536
	s_branch .LBB0_148

.LBB0_1329:
	v_mov_b32_e32 v0, v188
	v_mov_b32_e32 v2, 0x21d28
	v_readlane_b32 s0, v238, 7
	v_add_u32_e32 v2, 0, v2
	ds_read_b64 v[2:3], v2
	v_ashrrev_i32_e32 v1, 6, v0
	v_add_u32_e32 v28, s0, v1
	s_mov_b32 s0, 0xa000
	v_cmp_gt_i32_e32 vcc, s0, v28
	s_waitcnt lgkmcnt(0)
	v_readfirstlane_b32 s4, v2
	v_mov_b32_e32 v2, 0x21c40
	v_readfirstlane_b32 s2, v3
	v_add_u32_e32 v2, 0, v2
	ds_read_b64 v[2:3], v2
	s_waitcnt lgkmcnt(0)
	v_readfirstlane_b32 s6, v2
	v_mov_b32_e32 v2, 0x21d28
	v_readfirstlane_b32 s5, v3
	v_add_u32_e32 v2, 0, v2
	ds_read_b64 v[2:3], v2
	s_waitcnt lgkmcnt(0)
	v_readfirstlane_b32 s7, v3
	v_readfirstlane_b32 s8, v2
	s_and_saveexec_b64 s[0:1], vcc
	v_readlane_b32 s52, v236, 11
	v_readlane_b32 s44, v236, 3
	s_movk_i32 s50, 0x6000
	s_movk_i32 s48, 0x1fff
	v_readlane_b32 s53, v236, 12
	s_mov_b64 s[58:59], 0x1000
	v_readlane_b32 s45, v236, 4
	s_cbranch_execz .LBB0_1336
	s_add_u32 s8, s8, 0x6078000
	s_addc_u32 s9, s7, 0
	s_lshl_b32 s7, s52, 13
	s_add_u32 s6, s6, s7
	s_addc_u32 s5, s5, 0
	v_lshlrev_b32_e32 v1, 2, v0
	s_add_u32 s6, s6, 0x1000
	v_and_b32_e32 v30, 0xfc, v1
	s_addc_u32 s7, s5, 0
	v_lshlrev_b32_e32 v164, 2, v30
	v_or_b32_e32 v34, 0x100, v30
	v_lshl_add_u64 v[32:33], s[6:7], 0, v[164:165]
	v_lshlrev_b32_e32 v164, 2, v34
	v_or_b32_e32 v38, 0x200, v30
	v_lshl_add_u64 v[36:37], s[6:7], 0, v[164:165]
	v_lshlrev_b32_e32 v164, 2, v38
	v_or_b32_e32 v42, 0x300, v30
	v_ashrrev_i32_e32 v29, 31, v28
	v_lshl_add_u64 v[40:41], s[6:7], 0, v[164:165]
	v_lshlrev_b32_e32 v164, 2, v42
	v_lshlrev_b64 v[2:3], 11, v[28:29]
	v_and_b32_e32 v0, 63, v0
	s_movk_i32 s5, 0x80
	s_add_u32 s4, s4, 0x2bc3000
	v_lshl_add_u64 v[44:45], s[6:7], 0, v[164:165]
	v_lshlrev_b32_e32 v164, 1, v30
	v_lshl_or_b32 v2, v0, 3, v2
	v_lshlrev_b64 v[50:51], 12, v[28:29]
	v_bitop3_b32 v31, v1, s5, v193 bitop3:0x6c
	s_addc_u32 s5, s2, 0
	v_lshl_add_u64 v[46:47], s[8:9], 0, v[164:165]
	v_lshl_add_u64 v[48:49], s[8:9], 0, v[2:3]
	v_lshl_or_b32 v50, v0, 4, v50
	s_mov_b64 s[8:9], 0
	global_load_dwordx4 v[198:201], v[32:33], off
	global_load_dwordx4 v[202:205], v[36:37], off
	global_load_dwordx4 v[206:209], v[40:41], off
	global_load_dwordx4 v[210:213], v[44:45], off
	s_branch .LBB0_1332

.LBB0_1334:
	s_or_b64 exec, exec, s[10:11]
	s_waitcnt vmcnt(3)
	v_mov_b32_e32 v26, v21
	s_waitcnt vmcnt(2)
	v_mov_b32_e32 v27, v17
	v_mov_b32_e32 v24, v20
	v_mov_b32_e32 v25, v16
	v_pk_mul_f32 v[26:27], v[26:27], v[26:27]
	v_mov_b32_e32 v78, v22
	v_mov_b32_e32 v79, v18
	v_pk_fma_f32 v[24:25], v[24:25], v[24:25], v[26:27]
	v_mov_b32_e32 v80, v23
	v_pk_fma_f32 v[24:25], v[78:79], v[78:79], v[24:25]
	s_waitcnt vmcnt(1)
	v_mov_b32_e32 v78, v13
	s_waitcnt vmcnt(0)
	v_mov_b32_e32 v79, v9
	v_mov_b32_e32 v81, v19
	v_mov_b32_e32 v26, v12
	v_mov_b32_e32 v27, v8
	v_pk_mul_f32 v[78:79], v[78:79], v[78:79]
	v_pk_fma_f32 v[24:25], v[80:81], v[80:81], v[24:25]
	v_mov_b32_e32 v80, v14
	v_mov_b32_e32 v81, v10
	v_pk_fma_f32 v[26:27], v[26:27], v[26:27], v[78:79]
	v_mov_b32_e32 v82, v15
	v_mov_b32_e32 v83, v11
	v_pk_fma_f32 v[26:27], v[80:81], v[80:81], v[26:27]
	v_add_f32_e32 v24, v24, v25
	v_pk_fma_f32 v[26:27], v[82:83], v[82:83], v[26:27]
	s_nop 0
	v_add_f32_e32 v24, v24, v26
	v_add_f32_e32 v24, v24, v27
	ds_bpermute_b32 v25, v31, v24
	s_waitcnt lgkmcnt(0)
	v_add_f32_e32 v24, v24, v25
	ds_swizzle_b32 v25, v24 offset:swizzle(SWAP,16)
	s_waitcnt lgkmcnt(0)
	v_add_f32_e32 v24, v24, v25
	ds_swizzle_b32 v25, v24 offset:swizzle(SWAP,8)
	s_waitcnt lgkmcnt(0)
	v_add_f32_e32 v24, v24, v25
	ds_swizzle_b32 v25, v24 offset:swizzle(SWAP,4)
	s_waitcnt lgkmcnt(0)
	v_add_f32_e32 v24, v24, v25
	ds_swizzle_b32 v25, v24 offset:swizzle(SWAP,2)
	s_waitcnt lgkmcnt(0)
	v_add_f32_e32 v24, v24, v25
	ds_swizzle_b32 v25, v24 offset:swizzle(SWAP,1)
	s_waitcnt lgkmcnt(0)
	v_add_f32_e32 v24, v24, v25
	v_fmamk_f32 v24, v24, 0x3a800000, v189
	v_cmp_gt_f32_e64 s[34:35], s28, v24
	v_mul_f32_e32 v25, 0x4b800000, v24
	s_nop 0
	v_cndmask_b32_e64 v24, v24, v25, s[34:35]
	v_rsq_f32_e32 v24, v24
	s_nop 0
	v_mul_f32_e32 v25, 0x45800000, v24
	v_cndmask_b32_e64 v29, v24, v25, s[34:35]
	v_add_u32_e32 v24, 0xffffe000, v28
	v_lshrrev_b32_e32 v24, 12, v24
	v_add_u32_e32 v24, 1, v24
	v_cmp_lt_i32_e64 s[34:35], s48, v28
	v_mul_f32_e32 v20, v20, v29
	v_mul_f32_e32 v21, v21, v29
	v_cndmask_b32_e64 v24, 0, v24, s[34:35]
	v_add_u32_e32 v26, s86, v24
	v_mov_b64_e32 v[24:25], s[4:5]
	v_mad_u64_u32 v[78:79], s[6:7], v26, s50, v[24:25]
	v_lshl_add_u64 v[80:81], v[78:79], 0, s[58:59]
	v_lshl_add_u64 v[82:83], v[78:79], 0, v[164:165]
	v_lshl_add_u64 v[78:79], v[80:81], 0, v[164:165]
	v_mov_b32_e32 v252, v78
	v_mov_b32_e32 v253, v79
	global_load_dwordx4 v[214:217], v[82:83], off
	global_load_dwordx4 v[218:221], v[82:83], off offset:1024
	global_load_dwordx4 v[222:225], v[82:83], off offset:2048
	global_load_dwordx4 v[226:229], v[82:83], off offset:3072
	global_load_dwordx4 v[230:233], v[252:253], off
	global_load_dwordx4 v[240:243], v[252:253], off offset:1024
	global_load_dwordx4 v[244:247], v[252:253], off offset:2048
	global_load_dwordx4 v[248:251], v[252:253], off offset:3072
	s_waitcnt vmcnt(0)
	v_mov_b32_e32 v24, v198
	v_mov_b32_e32 v25, v199
	v_mov_b32_e32 v26, v200
	v_mov_b32_e32 v27, v201
	v_mov_b32_e32 v84, v214
	v_mov_b32_e32 v85, v215
	v_mov_b32_e32 v86, v216
	v_mov_b32_e32 v87, v217
	v_mov_b32_e32 v88, v230
	v_mov_b32_e32 v89, v231
	v_mov_b32_e32 v90, v232
	v_mov_b32_e32 v91, v233
	v_mul_f32_e32 v22, v22, v29
	v_mul_f32_e32 v23, v23, v29
	v_lshlrev_b32_e32 v78, 2, v34
	v_mov_b32_e32 v79, v165
	v_mul_f32_e32 v16, v16, v29
	v_mul_f32_e32 v17, v17, v29
	v_mul_f32_e32 v18, v18, v29
	v_mul_f32_e32 v19, v19, v29
	v_mul_f32_e32 v12, v12, v29
	v_mul_f32_e32 v13, v13, v29
	v_mul_f32_e32 v14, v14, v29
	v_mul_f32_e32 v15, v15, v29
	v_mul_f32_e32 v8, v8, v29
	v_mul_f32_e32 v9, v9, v29
	v_mul_f32_e32 v10, v10, v29
	v_mul_f32_e32 v11, v11, v29
	v_mul_f32_e32 v20, v24, v20
	v_mul_f32_e32 v21, v25, v21
	v_add_f32_e32 v24, 1.0, v88
	v_fma_f32 v20, v24, v20, v84
	v_add_f32_e32 v24, 1.0, v89
	v_fma_f32 v21, v24, v21, v85
	v_mul_f32_e32 v22, v26, v22
	v_add_f32_e32 v24, 1.0, v90
	v_fma_f32 v22, v22, v24, v86
	v_mul_f32_e32 v23, v27, v23
	v_add_f32_e32 v24, 1.0, v91
	v_fmac_f32_e32 v87, v23, v24
	v_cvt_pk_bf16_f32 v20, v20, v21
	v_cvt_pk_bf16_f32 v21, v22, v87
	global_store_dwordx2 v[48:49], v[20:21], off
	v_lshl_add_u64 v[84:85], v[80:81], 0, v[78:79]
	v_mov_b32_e32 v24, v202
	v_mov_b32_e32 v25, v203
	v_mov_b32_e32 v26, v204
	v_mov_b32_e32 v27, v205
	v_mov_b32_e32 v20, v218
	v_mov_b32_e32 v21, v219
	v_mov_b32_e32 v22, v220
	v_mov_b32_e32 v23, v221
	v_mul_f32_e32 v16, v16, v24
	v_mov_b32_e32 v84, v240
	v_mov_b32_e32 v85, v241
	v_mov_b32_e32 v86, v242
	v_mov_b32_e32 v87, v243
	v_mul_f32_e32 v17, v17, v25
	v_mul_f32_e32 v18, v18, v26
	v_mul_f32_e32 v19, v19, v27
	v_add_f32_e32 v24, 1.0, v84
	v_fma_f32 v16, v16, v24, v20
	v_add_f32_e32 v20, 1.0, v85
	v_fma_f32 v17, v17, v20, v21
	v_add_f32_e32 v20, 1.0, v86
	v_fma_f32 v18, v18, v20, v22
	v_add_f32_e32 v20, 1.0, v87
	v_fmac_f32_e32 v23, v19, v20
	v_lshlrev_b32_e32 v20, 2, v38
	v_mov_b32_e32 v21, v165
	v_cvt_pk_bf16_f32 v16, v16, v17
	v_cvt_pk_bf16_f32 v17, v18, v23
	global_store_dwordx2 v[48:49], v[16:17], off offset:512
	v_lshl_add_u64 v[26:27], v[80:81], 0, v[20:21]
	v_mov_b32_e32 v16, v206
	v_mov_b32_e32 v17, v207
	v_mov_b32_e32 v18, v208
	v_mov_b32_e32 v19, v209
	v_mov_b32_e32 v22, v222
	v_mov_b32_e32 v23, v223
	v_mov_b32_e32 v24, v224
	v_mov_b32_e32 v25, v225
	v_mov_b32_e32 v84, v244
	v_mov_b32_e32 v85, v245
	v_mov_b32_e32 v86, v246
	v_mov_b32_e32 v87, v247
	v_mul_f32_e32 v12, v12, v16
	v_mul_f32_e32 v13, v13, v17
	v_add_f32_e32 v16, 1.0, v84
	v_fma_f32 v12, v12, v16, v22
	v_add_f32_e32 v16, 1.0, v85
	v_fma_f32 v13, v13, v16, v23
	v_mul_f32_e32 v14, v14, v18
	v_add_f32_e32 v16, 1.0, v86
	v_fma_f32 v14, v14, v16, v24
	v_mul_f32_e32 v15, v15, v19
	v_add_f32_e32 v16, 1.0, v87
	v_fmac_f32_e32 v25, v15, v16
	v_lshlrev_b32_e32 v22, 2, v42
	v_mov_b32_e32 v23, v165
	v_cvt_pk_bf16_f32 v12, v12, v13
	v_cvt_pk_bf16_f32 v13, v14, v25
	global_store_dwordx2 v[48:49], v[12:13], off offset:1024
	v_lshl_add_u64 v[24:25], v[80:81], 0, v[22:23]
	v_mov_b32_e32 v16, v210
	v_mov_b32_e32 v17, v211
	v_mov_b32_e32 v18, v212
	v_mov_b32_e32 v19, v213
	v_mov_b32_e32 v12, v226
	v_mov_b32_e32 v13, v227
	v_mov_b32_e32 v14, v228
	v_mov_b32_e32 v15, v229
	v_mul_f32_e32 v8, v8, v16
	v_mov_b32_e32 v24, v248
	v_mov_b32_e32 v25, v249
	v_mov_b32_e32 v26, v250
	v_mov_b32_e32 v27, v251
	v_mul_f32_e32 v9, v9, v17
	v_mul_f32_e32 v10, v10, v18
	v_mul_f32_e32 v11, v11, v19
	v_add_f32_e32 v16, 1.0, v24
	v_fma_f32 v8, v8, v16, v12
	v_add_f32_e32 v12, 1.0, v25
	v_fma_f32 v9, v9, v12, v13
	v_add_f32_e32 v12, 1.0, v26
	v_fma_f32 v10, v10, v12, v14
	v_add_f32_e32 v12, 1.0, v27
	v_fmac_f32_e32 v15, v11, v12
	v_cvt_pk_bf16_f32 v8, v8, v9
	v_cvt_pk_bf16_f32 v9, v10, v15
	global_store_dwordx2 v[48:49], v[8:9], off offset:1536
	s_and_saveexec_b64 s[10:11], vcc
	s_cbranch_execz .LBB0_1331
	v_pk_mul_f32 v[8:9], v[76:77], v[76:77]
	v_pk_mul_f32 v[10:11], v[68:69], v[68:69]
	v_pk_fma_f32 v[8:9], v[74:75], v[74:75], v[8:9]
	v_pk_fma_f32 v[10:11], v[66:67], v[66:67], v[10:11]
	v_pk_fma_f32 v[8:9], v[72:73], v[72:73], v[8:9]
	v_pk_fma_f32 v[10:11], v[64:65], v[64:65], v[10:11]
	v_pk_fma_f32 v[8:9], v[70:71], v[70:71], v[8:9]
	v_pk_fma_f32 v[10:11], v[62:63], v[62:63], v[10:11]
	v_add_f32_e32 v8, v8, v9
	v_add_f32_e32 v8, v11, v8
	v_add_f32_e32 v8, v10, v8
	ds_bpermute_b32 v9, v31, v8
	v_lshlrev_b64 v[14:15], 11, v[60:61]
	s_waitcnt lgkmcnt(0)
	v_add_f32_e32 v8, v8, v9
	ds_swizzle_b32 v9, v8 offset:swizzle(SWAP,16)
	s_waitcnt lgkmcnt(0)
	v_add_f32_e32 v8, v8, v9
	ds_swizzle_b32 v9, v8 offset:swizzle(SWAP,8)
	s_waitcnt lgkmcnt(0)
	v_add_f32_e32 v8, v8, v9
	ds_swizzle_b32 v9, v8 offset:swizzle(SWAP,4)
	s_waitcnt lgkmcnt(0)
	v_add_f32_e32 v8, v8, v9
	ds_swizzle_b32 v9, v8 offset:swizzle(SWAP,2)
	s_waitcnt lgkmcnt(0)
	v_add_f32_e32 v8, v8, v9
	ds_swizzle_b32 v9, v8 offset:swizzle(SWAP,1)
	s_waitcnt lgkmcnt(0)
	v_add_f32_e32 v8, v8, v9
	v_fmamk_f32 v8, v8, 0x3a800000, v189
	v_cmp_gt_f32_e32 vcc, s28, v8
	v_mul_f32_e32 v9, 0x4b800000, v8
	s_nop 0
	v_cndmask_b32_e32 v8, v8, v9, vcc
	v_rsq_f32_e32 v8, v8
	s_nop 0
	v_mul_f32_e32 v9, 0x45800000, v8
	v_cndmask_b32_e32 v24, v8, v9, vcc
	v_add_u32_e32 v8, 0xffffe000, v60
	v_lshrrev_b32_e32 v8, 12, v8
	v_add_u32_e32 v8, 1, v8
	v_cmp_lt_i32_e32 vcc, s48, v60
	s_nop 1
	v_cndmask_b32_e32 v8, 0, v8, vcc
	v_add_u32_e32 v10, s86, v8
	v_mov_b64_e32 v[8:9], s[4:5]
	v_mad_u64_u32 v[8:9], s[6:7], v10, s50, v[8:9]
	v_lshl_add_u64 v[16:17], v[8:9], 0, s[58:59]
	v_lshl_add_u64 v[8:9], v[8:9], 0, v[164:165]
	v_lshl_add_u64 v[18:19], v[16:17], 0, v[164:165]
	v_mov_b32_e32 v254, v18
	v_mov_b32_e32 v255, v19
	global_load_dwordx4 v[214:217], v[8:9], off
	global_load_dwordx4 v[218:221], v[8:9], off offset:1024
	global_load_dwordx4 v[222:225], v[8:9], off offset:2048
	global_load_dwordx4 v[226:229], v[8:9], off offset:3072
	global_load_dwordx4 v[230:233], v[254:255], off
	global_load_dwordx4 v[240:243], v[254:255], off offset:1024
	global_load_dwordx4 v[244:247], v[254:255], off offset:2048
	global_load_dwordx4 v[248:251], v[254:255], off offset:3072
	s_waitcnt vmcnt(0)
	v_mov_b32_e32 v10, v198
	v_mov_b32_e32 v11, v199
	v_mov_b32_e32 v12, v200
	v_mov_b32_e32 v13, v201
	v_mov_b32_e32 v60, v214
	v_mov_b32_e32 v61, v215
	v_mov_b32_e32 v62, v216
	v_mov_b32_e32 v63, v217
	v_mov_b32_e32 v64, v230
	v_mov_b32_e32 v65, v231
	v_mov_b32_e32 v66, v232
	v_mov_b32_e32 v67, v233
	v_mul_f32_e32 v18, v5, v24
	v_mul_f32_e32 v10, v10, v18
	v_add_f32_e32 v18, 1.0, v64
	v_fma_f32 v10, v18, v10, v60
	v_mul_f32_e32 v18, v59, v24
	v_mul_f32_e32 v11, v11, v18
	v_add_f32_e32 v18, 1.0, v65
	v_fma_f32 v11, v18, v11, v61
	v_mul_f32_e32 v18, v7, v24
	v_mul_f32_e32 v12, v12, v18
	v_add_f32_e32 v18, 1.0, v66
	v_fma_f32 v12, v12, v18, v62
	v_mul_f32_e32 v18, v57, v24
	v_mul_f32_e32 v13, v13, v18
	v_add_f32_e32 v18, 1.0, v67
	v_fmac_f32_e32 v63, v13, v18
	v_lshl_add_u64 v[18:19], v[46:47], 0, v[14:15]
	v_cvt_pk_bf16_f32 v10, v10, v11
	v_cvt_pk_bf16_f32 v11, v12, v63
	global_store_dwordx2 v[18:19], v[10:11], off
	v_lshl_add_u64 v[14:15], v[16:17], 0, v[78:79]
	v_mov_b32_e32 v10, v202
	v_mov_b32_e32 v11, v203
	v_mov_b32_e32 v12, v204
	v_mov_b32_e32 v13, v205
	v_mov_b32_e32 v60, v218
	v_mov_b32_e32 v61, v219
	v_mov_b32_e32 v62, v220
	v_mov_b32_e32 v63, v221
	v_mov_b32_e32 v64, v240
	v_mov_b32_e32 v65, v241
	v_mov_b32_e32 v66, v242
	v_mov_b32_e32 v67, v243
	v_mul_f32_e32 v14, v4, v24
	v_mul_f32_e32 v10, v14, v10
	v_add_f32_e32 v14, 1.0, v64
	v_fma_f32 v10, v10, v14, v60
	v_mul_f32_e32 v14, v58, v24
	v_mul_f32_e32 v11, v14, v11
	v_add_f32_e32 v14, 1.0, v65
	v_fma_f32 v11, v11, v14, v61
	v_mul_f32_e32 v14, v6, v24
	v_mul_f32_e32 v12, v14, v12
	v_add_f32_e32 v14, 1.0, v66
	v_fma_f32 v12, v12, v14, v62
	v_mul_f32_e32 v14, v56, v24
	v_mul_f32_e32 v13, v14, v13
	v_add_f32_e32 v14, 1.0, v67
	v_fmac_f32_e32 v63, v13, v14
	v_cvt_pk_bf16_f32 v10, v10, v11
	v_cvt_pk_bf16_f32 v11, v12, v63
	global_store_dwordx2 v[18:19], v[10:11], off offset:512
	v_lshl_add_u64 v[14:15], v[16:17], 0, v[20:21]
	v_mov_b32_e32 v10, v206
	v_mov_b32_e32 v11, v207
	v_mov_b32_e32 v12, v208
	v_mov_b32_e32 v13, v209
	v_mov_b32_e32 v60, v222
	v_mov_b32_e32 v61, v223
	v_mov_b32_e32 v62, v224
	v_mov_b32_e32 v63, v225
	v_mov_b32_e32 v64, v244
	v_mov_b32_e32 v65, v245
	v_mov_b32_e32 v66, v246
	v_mov_b32_e32 v67, v247
	v_mul_f32_e32 v14, v1, v24
	v_lshl_add_u64 v[16:17], v[16:17], 0, v[22:23]
	v_mul_f32_e32 v10, v14, v10
	v_add_f32_e32 v14, 1.0, v64
	v_fma_f32 v10, v10, v14, v60
	v_mul_f32_e32 v14, v55, v24
	v_mul_f32_e32 v11, v14, v11
	v_add_f32_e32 v14, 1.0, v65
	v_fma_f32 v11, v11, v14, v61
	v_mul_f32_e32 v14, v3, v24
	v_mul_f32_e32 v12, v14, v12
	v_add_f32_e32 v14, 1.0, v66
	v_fma_f32 v12, v12, v14, v62
	v_mul_f32_e32 v14, v53, v24
	v_mul_f32_e32 v13, v14, v13
	v_add_f32_e32 v14, 1.0, v67
	v_fmac_f32_e32 v63, v13, v14
	v_cvt_pk_bf16_f32 v10, v10, v11
	v_cvt_pk_bf16_f32 v11, v12, v63
	global_store_dwordx2 v[18:19], v[10:11], off offset:1024
	v_mov_b32_e32 v12, v210
	v_mov_b32_e32 v13, v211
	v_mov_b32_e32 v14, v212
	v_mov_b32_e32 v15, v213
	s_nop 0
	v_mov_b32_e32 v8, v226
	v_mov_b32_e32 v9, v227
	v_mov_b32_e32 v10, v228
	v_mov_b32_e32 v11, v229
	s_nop 0
	v_mov_b32_e32 v20, v248
	v_mov_b32_e32 v21, v249
	v_mov_b32_e32 v22, v250
	v_mov_b32_e32 v23, v251
	v_mul_f32_e32 v16, v0, v24
	v_mul_f32_e32 v12, v16, v12
	v_add_f32_e32 v16, 1.0, v20
	v_fma_f32 v8, v12, v16, v8
	v_mul_f32_e32 v12, v54, v24
	v_mul_f32_e32 v12, v12, v13
	v_add_f32_e32 v13, 1.0, v21
	v_fma_f32 v9, v12, v13, v9
	v_mul_f32_e32 v12, v2, v24
	v_mul_f32_e32 v12, v12, v14
	v_add_f32_e32 v13, 1.0, v22
	v_fma_f32 v10, v12, v13, v10
	v_mul_f32_e32 v12, v52, v24
	v_mul_f32_e32 v12, v12, v15
	v_add_f32_e32 v13, 1.0, v23
	v_fmac_f32_e32 v11, v12, v13
	v_cvt_pk_bf16_f32 v8, v8, v9
	v_cvt_pk_bf16_f32 v9, v10, v11
	global_store_dwordx2 v[18:19], v[8:9], off offset:1536
	s_branch .LBB0_1331
